# DSA_IN QK rope epilogue batched table loads + pipelined indexer bisect ballots
# speedup vs baseline: 1.0119x; 1.0119x over previous
; DI bf16 f2bf(float a) { return (bf16)(pack2(a, 0.f) & 0xffffu); }
; DI int crow(int i, int g) { return (i & 3) + 8 * (i >> 2) + 4 * g; }
;     ...
;       if (nt < 16) {
;         bf16* dst = (bf16*)(ws + (nt < 8 ? OFF_Q : OFF_K));
;         const int hh = nt & 7;
; #pragma unroll
;         for (int j = 0; j < 2; ++j)
; #pragma unroll
;           for (int i = 0; i < 16; ++i) {
;             int s = s0 + crow(i, g);
;             int d = 32 * j + r;
;             float2 cs = t128[s * 64 + d];
;             float x1 = acc[j][i], x2 = acc[j + 2][i];
;             bf16* qp = dst + ((size_t)(bidx * 8 + hh) * 2048 + s) * 128;
;             qp[d] = f2bf(x1 * cs.x - x2 * cs.y);
;             qp[d + 64] = f2bf(x2 * cs.x + x1 * cs.y);
;           }
.LBB0_998:
	v_or_b32_e32 v68, v130, v154
	v_lshlrev_b32_e32 v72, 6, v68
	v_or_b32_e32 v64, v72, v128
	v_mov_b32_e32 v65, 0
	s_mov_b64 s[6:7], 0x1000
	v_lshl_add_u64 v[202:203], v[64:65], 3, s[18:19]
	v_lshl_add_u64 v[204:205], v[202:203], 0, s[6:7]
	v_lshl_add_u64 v[206:207], v[204:205], 0, s[6:7]
	v_lshl_add_u64 v[208:209], v[206:207], 0, s[6:7]
	global_load_dwordx2 v[92:93], v[202:203], off
	global_load_dwordx2 v[94:95], v[202:203], off offset:256
	global_load_dwordx2 v[96:97], v[202:203], off offset:512
	global_load_dwordx2 v[98:99], v[202:203], off offset:768
	global_load_dwordx2 v[100:101], v[202:203], off offset:1024
	global_load_dwordx2 v[102:103], v[202:203], off offset:1280
	global_load_dwordx2 v[104:105], v[202:203], off offset:1536
	global_load_dwordx2 v[106:107], v[202:203], off offset:1792
	global_load_dwordx2 v[108:109], v[204:205], off
	global_load_dwordx2 v[110:111], v[204:205], off offset:256
	global_load_dwordx2 v[112:113], v[204:205], off offset:512
	global_load_dwordx2 v[114:115], v[204:205], off offset:768
	global_load_dwordx2 v[116:117], v[204:205], off offset:1024
	global_load_dwordx2 v[118:119], v[204:205], off offset:1280
	global_load_dwordx2 v[120:121], v[204:205], off offset:1536
	global_load_dwordx2 v[122:123], v[204:205], off offset:1792
	global_load_dwordx2 v[124:125], v[206:207], off
	global_load_dwordx2 v[126:127], v[206:207], off offset:256
	global_load_dwordx2 v[174:175], v[206:207], off offset:512
	global_load_dwordx2 v[176:177], v[206:207], off offset:768
	global_load_dwordx2 v[178:179], v[206:207], off offset:1024
	global_load_dwordx2 v[180:181], v[206:207], off offset:1280
	global_load_dwordx2 v[182:183], v[206:207], off offset:1536
	global_load_dwordx2 v[184:185], v[206:207], off offset:1792
	global_load_dwordx2 v[186:187], v[208:209], off
	global_load_dwordx2 v[188:189], v[208:209], off offset:256
	global_load_dwordx2 v[190:191], v[208:209], off offset:512
	global_load_dwordx2 v[192:193], v[208:209], off offset:768
	global_load_dwordx2 v[194:195], v[208:209], off offset:1024
	global_load_dwordx2 v[196:197], v[208:209], off offset:1280
	global_load_dwordx2 v[198:199], v[208:209], off offset:1536
	global_load_dwordx2 v[200:201], v[208:209], off offset:1792
	s_cmp_lt_i32 s4, 8
	s_cselect_b32 s5, s64, 0x13000000
	s_add_u32 s6, s22, s5
	s_addc_u32 s7, s23, 0
	s_and_b32 s4, s4, 7
	s_lshl_b32 s5, s30, 3
	s_or_b32 s4, s5, s4
	s_ashr_i32 s5, s4, 31
	s_lshl_b64 s[4:5], s[4:5], 19
	s_add_u32 s4, s6, s4
	s_addc_u32 s5, s7, s5
	v_lshlrev_b32_e32 v130, 1, v128
	v_lshl_add_u64 v[70:71], s[4:5], 0, v[130:131]
	v_lshlrev_b32_e32 v66, 8, v68
	v_mov_b32_e32 v67, 0
	s_mov_b64 s[6:7], 0x1000
	v_lshl_add_u64 v[210:211], v[66:67], 0, v[70:71]
	v_lshl_add_u64 v[212:213], v[210:211], 0, s[6:7]
	s_waitcnt vmcnt(31)
	v_mul_f32_e32 v214, v32, v93
	v_mul_f32_e32 v215, v48, v93
	v_fma_f32 v214, v48, v92, -v214
	v_fmac_f32_e32 v215, v32, v92
	v_cvt_pk_bf16_f32 v214, v214, v214
	v_cvt_pk_bf16_f32 v215, v215, v215
	global_store_short v[210:211], v214, off
	global_store_short v[210:211], v215, off offset:128
	s_waitcnt vmcnt(32)
	v_mul_f32_e32 v216, v0, v95
	v_mul_f32_e32 v217, v16, v95
	v_fma_f32 v216, v16, v94, -v216
	v_fmac_f32_e32 v217, v0, v94
	v_cvt_pk_bf16_f32 v216, v216, v216
	v_cvt_pk_bf16_f32 v217, v217, v217
	global_store_short v[210:211], v216, off offset:64
	global_store_short v[210:211], v217, off offset:192
	s_waitcnt vmcnt(33)
	v_mul_f32_e32 v214, v33, v97
	v_mul_f32_e32 v215, v49, v97
	v_fma_f32 v214, v49, v96, -v214
	v_fmac_f32_e32 v215, v33, v96
	v_cvt_pk_bf16_f32 v214, v214, v214
	v_cvt_pk_bf16_f32 v215, v215, v215
	global_store_short v[210:211], v214, off offset:256
	global_store_short v[210:211], v215, off offset:384
	s_waitcnt vmcnt(34)
	v_mul_f32_e32 v216, v1, v99
	v_mul_f32_e32 v217, v17, v99
	v_fma_f32 v216, v17, v98, -v216
	v_fmac_f32_e32 v217, v1, v98
	v_cvt_pk_bf16_f32 v216, v216, v216
	v_cvt_pk_bf16_f32 v217, v217, v217
	global_store_short v[210:211], v216, off offset:320
	global_store_short v[210:211], v217, off offset:448
	s_waitcnt vmcnt(35)
	v_mul_f32_e32 v214, v34, v101
	v_mul_f32_e32 v215, v50, v101
	v_fma_f32 v214, v50, v100, -v214
	v_fmac_f32_e32 v215, v34, v100
	v_cvt_pk_bf16_f32 v214, v214, v214
	v_cvt_pk_bf16_f32 v215, v215, v215
	global_store_short v[210:211], v214, off offset:512
	global_store_short v[210:211], v215, off offset:640
	s_waitcnt vmcnt(36)
	v_mul_f32_e32 v216, v2, v103
	v_mul_f32_e32 v217, v18, v103
	v_fma_f32 v216, v18, v102, -v216
	v_fmac_f32_e32 v217, v2, v102
	v_cvt_pk_bf16_f32 v216, v216, v216
	v_cvt_pk_bf16_f32 v217, v217, v217
	global_store_short v[210:211], v216, off offset:576
	global_store_short v[210:211], v217, off offset:704
	s_waitcnt vmcnt(37)
	v_mul_f32_e32 v214, v35, v105
	v_mul_f32_e32 v215, v51, v105
	v_fma_f32 v214, v51, v104, -v214
	v_fmac_f32_e32 v215, v35, v104
	v_cvt_pk_bf16_f32 v214, v214, v214
	v_cvt_pk_bf16_f32 v215, v215, v215
	global_store_short v[210:211], v214, off offset:768
	global_store_short v[210:211], v215, off offset:896
	s_waitcnt vmcnt(38)
	v_mul_f32_e32 v216, v3, v107
	v_mul_f32_e32 v217, v19, v107
	v_fma_f32 v216, v19, v106, -v216
	v_fmac_f32_e32 v217, v3, v106
	v_cvt_pk_bf16_f32 v216, v216, v216
	v_cvt_pk_bf16_f32 v217, v217, v217
	global_store_short v[210:211], v216, off offset:832
	global_store_short v[210:211], v217, off offset:960
	s_waitcnt vmcnt(39)
	v_mul_f32_e32 v214, v36, v109
	v_mul_f32_e32 v215, v52, v109
	v_fma_f32 v214, v52, v108, -v214
	v_fmac_f32_e32 v215, v36, v108
	v_cvt_pk_bf16_f32 v214, v214, v214
	v_cvt_pk_bf16_f32 v215, v215, v215
	global_store_short v[210:211], v214, off offset:2048
	global_store_short v[210:211], v215, off offset:2176
	s_waitcnt vmcnt(40)
; DI bf16 f2bf(float a) { return (bf16)(pack2(a, 0.f) & 0xffffu); }
; DI int crow(int i, int g) { return (i & 3) + 8 * (i >> 2) + 4 * g; }
;     ...
;       if (nt < 16) {
;         bf16* dst = (bf16*)(ws + (nt < 8 ? OFF_Q : OFF_K));
;         const int hh = nt & 7;
; #pragma unroll
;         for (int j = 0; j < 2; ++j)
; #pragma unroll
;           for (int i = 0; i < 16; ++i) {
;             int s = s0 + crow(i, g);
;             int d = 32 * j + r;
;             float2 cs = t128[s * 64 + d];
;             float x1 = acc[j][i], x2 = acc[j + 2][i];
;             bf16* qp = dst + ((size_t)(bidx * 8 + hh) * 2048 + s) * 128;
;             qp[d] = f2bf(x1 * cs.x - x2 * cs.y);
;             qp[d + 64] = f2bf(x2 * cs.x + x1 * cs.y);
;           }
	v_mul_f32_e32 v216, v4, v111
	v_mul_f32_e32 v217, v20, v111
	v_fma_f32 v216, v20, v110, -v216
	v_fmac_f32_e32 v217, v4, v110
	v_cvt_pk_bf16_f32 v216, v216, v216
	v_cvt_pk_bf16_f32 v217, v217, v217
	global_store_short v[210:211], v216, off offset:2112
	global_store_short v[210:211], v217, off offset:2240
	s_waitcnt vmcnt(41)
	v_mul_f32_e32 v214, v37, v113
	v_mul_f32_e32 v215, v53, v113
	v_fma_f32 v214, v53, v112, -v214
	v_fmac_f32_e32 v215, v37, v112
	v_cvt_pk_bf16_f32 v214, v214, v214
	v_cvt_pk_bf16_f32 v215, v215, v215
	global_store_short v[210:211], v214, off offset:2304
	global_store_short v[210:211], v215, off offset:2432
	s_waitcnt vmcnt(42)
	v_mul_f32_e32 v216, v5, v115
	v_mul_f32_e32 v217, v21, v115
	v_fma_f32 v216, v21, v114, -v216
	v_fmac_f32_e32 v217, v5, v114
	v_cvt_pk_bf16_f32 v216, v216, v216
	v_cvt_pk_bf16_f32 v217, v217, v217
	global_store_short v[210:211], v216, off offset:2368
	global_store_short v[210:211], v217, off offset:2496
	s_waitcnt vmcnt(43)
	v_mul_f32_e32 v214, v38, v117
	v_mul_f32_e32 v215, v54, v117
	v_fma_f32 v214, v54, v116, -v214
	v_fmac_f32_e32 v215, v38, v116
	v_cvt_pk_bf16_f32 v214, v214, v214
	v_cvt_pk_bf16_f32 v215, v215, v215
	global_store_short v[210:211], v214, off offset:2560
	global_store_short v[210:211], v215, off offset:2688
	s_waitcnt vmcnt(44)
	v_mul_f32_e32 v216, v6, v119
	v_mul_f32_e32 v217, v22, v119
	v_fma_f32 v216, v22, v118, -v216
	v_fmac_f32_e32 v217, v6, v118
	v_cvt_pk_bf16_f32 v216, v216, v216
	v_cvt_pk_bf16_f32 v217, v217, v217
	global_store_short v[210:211], v216, off offset:2624
	global_store_short v[210:211], v217, off offset:2752
	s_waitcnt vmcnt(45)
	v_mul_f32_e32 v214, v39, v121
	v_mul_f32_e32 v215, v55, v121
	v_fma_f32 v214, v55, v120, -v214
	v_fmac_f32_e32 v215, v39, v120
	v_cvt_pk_bf16_f32 v214, v214, v214
	v_cvt_pk_bf16_f32 v215, v215, v215
	global_store_short v[210:211], v214, off offset:2816
	global_store_short v[210:211], v215, off offset:2944
	s_waitcnt vmcnt(46)
	v_mul_f32_e32 v216, v7, v123
	v_mul_f32_e32 v217, v23, v123
	v_fma_f32 v216, v23, v122, -v216
	v_fmac_f32_e32 v217, v7, v122
	v_cvt_pk_bf16_f32 v216, v216, v216
	v_cvt_pk_bf16_f32 v217, v217, v217
	global_store_short v[210:211], v216, off offset:2880
	global_store_short v[210:211], v217, off offset:3008
	s_waitcnt vmcnt(47)
	v_mul_f32_e32 v214, v40, v125
	v_mul_f32_e32 v215, v56, v125
	v_fma_f32 v214, v56, v124, -v214
	v_fmac_f32_e32 v215, v40, v124
	v_cvt_pk_bf16_f32 v214, v214, v214
	v_cvt_pk_bf16_f32 v215, v215, v215
	global_store_short v[212:213], v214, off
	global_store_short v[212:213], v215, off offset:128
	s_waitcnt vmcnt(48)
	v_mul_f32_e32 v216, v8, v127
	v_mul_f32_e32 v217, v24, v127
	v_fma_f32 v216, v24, v126, -v216
	v_fmac_f32_e32 v217, v8, v126
	v_cvt_pk_bf16_f32 v216, v216, v216
	v_cvt_pk_bf16_f32 v217, v217, v217
	global_store_short v[212:213], v216, off offset:64
	global_store_short v[212:213], v217, off offset:192
	s_waitcnt vmcnt(49)
	v_mul_f32_e32 v214, v41, v175
	v_mul_f32_e32 v215, v57, v175
	v_fma_f32 v214, v57, v174, -v214
	v_fmac_f32_e32 v215, v41, v174
	v_cvt_pk_bf16_f32 v214, v214, v214
	v_cvt_pk_bf16_f32 v215, v215, v215
	global_store_short v[212:213], v214, off offset:256
	global_store_short v[212:213], v215, off offset:384
	s_waitcnt vmcnt(50)
	v_mul_f32_e32 v216, v9, v177
	v_mul_f32_e32 v217, v25, v177
	v_fma_f32 v216, v25, v176, -v216
	v_fmac_f32_e32 v217, v9, v176
	v_cvt_pk_bf16_f32 v216, v216, v216
	v_cvt_pk_bf16_f32 v217, v217, v217
	global_store_short v[212:213], v216, off offset:320
	global_store_short v[212:213], v217, off offset:448
	s_waitcnt vmcnt(51)
	v_mul_f32_e32 v214, v42, v179
	v_mul_f32_e32 v215, v58, v179
	v_fma_f32 v214, v58, v178, -v214
	v_fmac_f32_e32 v215, v42, v178
	v_cvt_pk_bf16_f32 v214, v214, v214
	v_cvt_pk_bf16_f32 v215, v215, v215
	global_store_short v[212:213], v214, off offset:512
	global_store_short v[212:213], v215, off offset:640
	s_waitcnt vmcnt(52)
; DI bf16 f2bf(float a) { return (bf16)(pack2(a, 0.f) & 0xffffu); }
; DI int crow(int i, int g) { return (i & 3) + 8 * (i >> 2) + 4 * g; }
;     ...
;       if (nt < 16) {
;         bf16* dst = (bf16*)(ws + (nt < 8 ? OFF_Q : OFF_K));
;         const int hh = nt & 7;
; #pragma unroll
;         for (int j = 0; j < 2; ++j)
; #pragma unroll
;           for (int i = 0; i < 16; ++i) {
;             int s = s0 + crow(i, g);
;             int d = 32 * j + r;
;             float2 cs = t128[s * 64 + d];
;             float x1 = acc[j][i], x2 = acc[j + 2][i];
;             bf16* qp = dst + ((size_t)(bidx * 8 + hh) * 2048 + s) * 128;
;             qp[d] = f2bf(x1 * cs.x - x2 * cs.y);
;             qp[d + 64] = f2bf(x2 * cs.x + x1 * cs.y);
;           }
	v_mul_f32_e32 v216, v10, v181
	v_mul_f32_e32 v217, v26, v181
	v_fma_f32 v216, v26, v180, -v216
	v_fmac_f32_e32 v217, v10, v180
	v_cvt_pk_bf16_f32 v216, v216, v216
	v_cvt_pk_bf16_f32 v217, v217, v217
	global_store_short v[212:213], v216, off offset:576
	global_store_short v[212:213], v217, off offset:704
	s_waitcnt vmcnt(53)
	v_mul_f32_e32 v214, v43, v183
	v_mul_f32_e32 v215, v59, v183
	v_fma_f32 v214, v59, v182, -v214
	v_fmac_f32_e32 v215, v43, v182
	v_cvt_pk_bf16_f32 v214, v214, v214
	v_cvt_pk_bf16_f32 v215, v215, v215
	global_store_short v[212:213], v214, off offset:768
	global_store_short v[212:213], v215, off offset:896
	s_waitcnt vmcnt(54)
	v_mul_f32_e32 v216, v11, v185
	v_mul_f32_e32 v217, v27, v185
	v_fma_f32 v216, v27, v184, -v216
	v_fmac_f32_e32 v217, v11, v184
	v_cvt_pk_bf16_f32 v216, v216, v216
	v_cvt_pk_bf16_f32 v217, v217, v217
	global_store_short v[212:213], v216, off offset:832
	global_store_short v[212:213], v217, off offset:960
	s_waitcnt vmcnt(55)
	v_mul_f32_e32 v214, v44, v187
	v_mul_f32_e32 v215, v60, v187
	v_fma_f32 v214, v60, v186, -v214
	v_fmac_f32_e32 v215, v44, v186
	v_cvt_pk_bf16_f32 v214, v214, v214
	v_cvt_pk_bf16_f32 v215, v215, v215
	global_store_short v[212:213], v214, off offset:2048
	global_store_short v[212:213], v215, off offset:2176
	s_waitcnt vmcnt(56)
	v_mul_f32_e32 v216, v12, v189
	v_mul_f32_e32 v217, v28, v189
	v_fma_f32 v216, v28, v188, -v216
	v_fmac_f32_e32 v217, v12, v188
	v_cvt_pk_bf16_f32 v216, v216, v216
	v_cvt_pk_bf16_f32 v217, v217, v217
	global_store_short v[212:213], v216, off offset:2112
	global_store_short v[212:213], v217, off offset:2240
	s_waitcnt vmcnt(57)
	v_mul_f32_e32 v214, v45, v191
	v_mul_f32_e32 v215, v61, v191
	v_fma_f32 v214, v61, v190, -v214
	v_fmac_f32_e32 v215, v45, v190
	v_cvt_pk_bf16_f32 v214, v214, v214
	v_cvt_pk_bf16_f32 v215, v215, v215
	global_store_short v[212:213], v214, off offset:2304
	global_store_short v[212:213], v215, off offset:2432
	s_waitcnt vmcnt(58)
	v_mul_f32_e32 v216, v13, v193
	v_mul_f32_e32 v217, v29, v193
	v_fma_f32 v216, v29, v192, -v216
	v_fmac_f32_e32 v217, v13, v192
	v_cvt_pk_bf16_f32 v216, v216, v216
	v_cvt_pk_bf16_f32 v217, v217, v217
	global_store_short v[212:213], v216, off offset:2368
	global_store_short v[212:213], v217, off offset:2496
	s_waitcnt vmcnt(59)
	v_mul_f32_e32 v214, v46, v195
	v_mul_f32_e32 v215, v62, v195
	v_fma_f32 v214, v62, v194, -v214
	v_fmac_f32_e32 v215, v46, v194
	v_cvt_pk_bf16_f32 v214, v214, v214
	v_cvt_pk_bf16_f32 v215, v215, v215
	global_store_short v[212:213], v214, off offset:2560
	global_store_short v[212:213], v215, off offset:2688
	s_waitcnt vmcnt(60)
	v_mul_f32_e32 v216, v14, v197
	v_mul_f32_e32 v217, v30, v197
	v_fma_f32 v216, v30, v196, -v216
	v_fmac_f32_e32 v217, v14, v196
	v_cvt_pk_bf16_f32 v216, v216, v216
	v_cvt_pk_bf16_f32 v217, v217, v217
	global_store_short v[212:213], v216, off offset:2624
	global_store_short v[212:213], v217, off offset:2752
	s_waitcnt vmcnt(61)
	v_mul_f32_e32 v214, v47, v199
	v_mul_f32_e32 v215, v63, v199
	v_fma_f32 v214, v63, v198, -v214
	v_fmac_f32_e32 v215, v47, v198
	v_cvt_pk_bf16_f32 v214, v214, v214
	v_cvt_pk_bf16_f32 v215, v215, v215
	global_store_short v[212:213], v214, off offset:2816
	global_store_short v[212:213], v215, off offset:2944
	s_waitcnt vmcnt(62)
	v_mul_f32_e32 v216, v15, v201
	v_mul_f32_e32 v217, v31, v201
	v_fma_f32 v216, v31, v200, -v216
	v_fmac_f32_e32 v217, v15, v200
	v_cvt_pk_bf16_f32 v216, v216, v216
	v_cvt_pk_bf16_f32 v217, v217, v217
	global_store_short v[212:213], v216, off offset:2880
	global_store_short v[212:213], v217, off offset:3008
	s_branch .LBB0_945

; DI int ballot_cnt_ge(u32 a, u32 b) {
;   int t;
;   asm volatile("v_cmp_ge_u32 vcc, %1, %2\n\ts_bcnt1_i32_b64 %0, vcc" : "=s"(t) : "v"(a), "v"(b) : "vcc", "scc");
;   return t;
; }
; template <int NJ>
; DI u32 bisect256(const u32* row, int lane, int nw) {
;   u32 v[NJ];
; #pragma unroll
;   for (int j = 0; j < NJ; ++j) v[j] = (j < nw) ? row[j * 66 + lane + (lane >> 5)] : 0u;
;   u32 Tt = 0u;
;     ...
;     const u32 cand = Tt | (1u << bit);
;     int cnt = 0;
; #pragma unroll
;     for (int j = 0; j < NJ; ++j) cnt += ballot_cnt_ge(v[j], cand);
;     if (cnt >= 256) Tt = cand;
;   }
;   return Tt;
; }
.LBB0_1084:
	s_lshl_b32 s0, 1, s7
	s_or_b32 s28, s0, s6
	v_mov_b32_e32 v35, s28
	s_waitcnt lgkmcnt(11)
	v_cmp_ge_u32_e32 vcc, v0, v35
	v_cmp_ge_u32_e64 s[98:99], v1, v35
	v_cmp_ge_u32_e64 s[100:101], v2, v35
	s_bcnt1_i32_b64 s1, vcc
	s_bcnt1_i32_b64 s30, s[98:99]
	s_bcnt1_i32_b64 s32, s[100:101]
	s_add_i32 s0, s1, s30
	s_add_i32 s0, s0, s32
	s_waitcnt lgkmcnt(9)
	v_cmp_ge_u32_e32 vcc, v3, v35
	v_cmp_ge_u32_e64 s[98:99], v26, v35
	v_cmp_ge_u32_e64 s[100:101], v4, v35
	s_bcnt1_i32_b64 s1, vcc
	s_bcnt1_i32_b64 s30, s[98:99]
	s_bcnt1_i32_b64 s32, s[100:101]
	s_add_i32 s0, s0, s1
	s_add_i32 s0, s0, s30
	s_add_i32 s0, s0, s32
	s_waitcnt lgkmcnt(8)
	v_cmp_ge_u32_e32 vcc, v5, v35
	v_cmp_ge_u32_e64 s[98:99], v6, v35
	v_cmp_ge_u32_e64 s[100:101], v7, v35
	s_bcnt1_i32_b64 s1, vcc
	s_bcnt1_i32_b64 s30, s[98:99]
	s_bcnt1_i32_b64 s32, s[100:101]
	s_add_i32 s0, s0, s1
	s_add_i32 s0, s0, s30
	s_add_i32 s0, s0, s32
	s_waitcnt lgkmcnt(6)
	v_cmp_ge_u32_e32 vcc, v8, v35
	v_cmp_ge_u32_e64 s[98:99], v9, v35
	v_cmp_ge_u32_e64 s[100:101], v10, v35
	s_bcnt1_i32_b64 s1, vcc
	s_bcnt1_i32_b64 s30, s[98:99]
	s_bcnt1_i32_b64 s32, s[100:101]
	s_add_i32 s0, s0, s1
	s_add_i32 s0, s0, s30
	s_add_i32 s0, s0, s32
	s_waitcnt lgkmcnt(5)
	v_cmp_ge_u32_e32 vcc, v11, v35
	v_cmp_ge_u32_e64 s[98:99], v12, v35
	v_cmp_ge_u32_e64 s[100:101], v13, v35
	s_bcnt1_i32_b64 s1, vcc
	s_bcnt1_i32_b64 s30, s[98:99]
	s_bcnt1_i32_b64 s32, s[100:101]
	s_add_i32 s0, s0, s1
	s_add_i32 s0, s0, s30
	s_add_i32 s0, s0, s32
	s_waitcnt lgkmcnt(3)
	v_cmp_ge_u32_e32 vcc, v14, v35
	v_cmp_ge_u32_e64 s[98:99], v15, v35
	v_cmp_ge_u32_e64 s[100:101], v16, v35
	s_bcnt1_i32_b64 s1, vcc
	s_bcnt1_i32_b64 s30, s[98:99]
	s_bcnt1_i32_b64 s32, s[100:101]
	s_add_i32 s0, s0, s1
	s_add_i32 s0, s0, s30
	s_add_i32 s0, s0, s32
	s_waitcnt lgkmcnt(2)
	v_cmp_ge_u32_e32 vcc, v17, v35
	v_cmp_ge_u32_e64 s[98:99], v18, v35
	v_cmp_ge_u32_e64 s[100:101], v19, v35
	s_bcnt1_i32_b64 s1, vcc
	s_bcnt1_i32_b64 s30, s[98:99]
	s_bcnt1_i32_b64 s32, s[100:101]
	s_add_i32 s0, s0, s1
	s_add_i32 s0, s0, s30
	s_add_i32 s0, s0, s32
	s_waitcnt lgkmcnt(0)
	v_cmp_ge_u32_e32 vcc, v20, v35
	v_cmp_ge_u32_e64 s[98:99], v21, v35
	v_cmp_ge_u32_e64 s[100:101], v22, v35
	s_bcnt1_i32_b64 s1, vcc
	s_bcnt1_i32_b64 s30, s[98:99]
	s_bcnt1_i32_b64 s32, s[100:101]
	s_add_i32 s0, s0, s1
	s_add_i32 s0, s0, s30
	s_add_i32 s0, s0, s32
	v_cmp_ge_u32_e32 vcc, v23, v35
	v_cmp_ge_u32_e64 s[98:99], v29, v35
	v_cmp_ge_u32_e64 s[100:101], v28, v35
	s_bcnt1_i32_b64 s1, vcc
	s_bcnt1_i32_b64 s30, s[98:99]
	s_bcnt1_i32_b64 s32, s[100:101]
	s_add_i32 s0, s0, s1
	s_add_i32 s0, s0, s30
	s_add_i32 s0, s0, s32
	v_cmp_ge_u32_e32 vcc, v31, v35
	v_cmp_ge_u32_e64 s[98:99], v30, v35
	v_cmp_ge_u32_e64 s[100:101], v33, v35
	s_bcnt1_i32_b64 s1, vcc
	s_bcnt1_i32_b64 s30, s[98:99]
	s_bcnt1_i32_b64 s32, s[100:101]
	s_add_i32 s0, s0, s1
	s_add_i32 s0, s0, s30
	s_add_i32 s0, s0, s32
	v_cmp_ge_u32_e32 vcc, v32, v35
	v_cmp_ge_u32_e64 s[98:99], v34, v35
	s_bcnt1_i32_b64 s1, vcc
	s_bcnt1_i32_b64 s30, s[98:99]
	s_add_i32 s0, s0, s1
	s_add_i32 s0, s0, s30
	s_cmpk_gt_i32 s0, 0xff
	s_cselect_b32 s6, s28, s6
	s_add_i32 s7, s7, -1
	s_cmp_lg_u32 s7, -1
	s_cbranch_scc1 .LBB0_1084
	s_mov_b64 s[28:29], 0

; DI int ballot_cnt_ge(u32 a, u32 b) {
;   int t;
;   asm volatile("v_cmp_ge_u32 vcc, %1, %2\n\ts_bcnt1_i32_b64 %0, vcc" : "=s"(t) : "v"(a), "v"(b) : "vcc", "scc");
;   return t;
; }
; template <int NJ>
; DI u32 bisect256(const u32* row, int lane, int nw) {
;   u32 v[NJ];
; #pragma unroll
;   for (int j = 0; j < NJ; ++j) v[j] = (j < nw) ? row[j * 66 + lane + (lane >> 5)] : 0u;
;   u32 Tt = 0u;
;     ...
;     const u32 cand = Tt | (1u << bit);
;     int cnt = 0;
; #pragma unroll
;     for (int j = 0; j < NJ; ++j) cnt += ballot_cnt_ge(v[j], cand);
;     if (cnt >= 256) Tt = cand;
;   }
;   return Tt;
; }
.LBB0_1096:
	s_lshl_b32 s28, 1, s7
	s_or_b32 s28, s28, s6
	v_mov_b32_e32 v23, s28
	s_waitcnt lgkmcnt(7)
	v_cmp_ge_u32_e32 vcc, v0, v23
	v_cmp_ge_u32_e64 s[98:99], v1, v23
	v_cmp_ge_u32_e64 s[100:101], v2, v23
	s_bcnt1_i32_b64 s1, vcc
	s_bcnt1_i32_b64 s30, s[98:99]
	s_bcnt1_i32_b64 s32, s[100:101]
	s_add_i32 s0, s1, s30
	s_add_i32 s0, s0, s32
	s_waitcnt lgkmcnt(5)
	v_cmp_ge_u32_e32 vcc, v3, v23
	v_cmp_ge_u32_e64 s[98:99], v26, v23
	v_cmp_ge_u32_e64 s[100:101], v4, v23
	s_bcnt1_i32_b64 s1, vcc
	s_bcnt1_i32_b64 s30, s[98:99]
	s_bcnt1_i32_b64 s32, s[100:101]
	s_add_i32 s0, s0, s1
	s_add_i32 s0, s0, s30
	s_add_i32 s0, s0, s32
	s_waitcnt lgkmcnt(4)
	v_cmp_ge_u32_e32 vcc, v5, v23
	v_cmp_ge_u32_e64 s[98:99], v6, v23
	v_cmp_ge_u32_e64 s[100:101], v7, v23
	s_bcnt1_i32_b64 s1, vcc
	s_bcnt1_i32_b64 s30, s[98:99]
	s_bcnt1_i32_b64 s32, s[100:101]
	s_add_i32 s0, s0, s1
	s_add_i32 s0, s0, s30
	s_add_i32 s0, s0, s32
	s_waitcnt lgkmcnt(2)
	v_cmp_ge_u32_e32 vcc, v8, v23
	v_cmp_ge_u32_e64 s[98:99], v9, v23
	v_cmp_ge_u32_e64 s[100:101], v10, v23
	s_bcnt1_i32_b64 s1, vcc
	s_bcnt1_i32_b64 s30, s[98:99]
	s_bcnt1_i32_b64 s32, s[100:101]
	s_add_i32 s0, s0, s1
	s_add_i32 s0, s0, s30
	s_add_i32 s0, s0, s32
	s_waitcnt lgkmcnt(1)
	v_cmp_ge_u32_e32 vcc, v11, v23
	v_cmp_ge_u32_e64 s[98:99], v12, v23
	v_cmp_ge_u32_e64 s[100:101], v13, v23
	s_bcnt1_i32_b64 s1, vcc
	s_bcnt1_i32_b64 s30, s[98:99]
	s_bcnt1_i32_b64 s32, s[100:101]
	s_add_i32 s0, s0, s1
	s_add_i32 s0, s0, s30
	s_add_i32 s0, s0, s32
	s_waitcnt lgkmcnt(0)
	v_cmp_ge_u32_e32 vcc, v14, v23
	v_cmp_ge_u32_e64 s[98:99], v15, v23
	v_cmp_ge_u32_e64 s[100:101], v17, v23
	s_bcnt1_i32_b64 s1, vcc
	s_bcnt1_i32_b64 s30, s[98:99]
	s_bcnt1_i32_b64 s32, s[100:101]
	s_add_i32 s0, s0, s1
	s_add_i32 s0, s0, s30
	s_add_i32 s0, s0, s32
	v_cmp_ge_u32_e32 vcc, v16, v23
	v_cmp_ge_u32_e64 s[98:99], v19, v23
	v_cmp_ge_u32_e64 s[100:101], v18, v23
	s_bcnt1_i32_b64 s1, vcc
	s_bcnt1_i32_b64 s30, s[98:99]
	s_bcnt1_i32_b64 s32, s[100:101]
	s_add_i32 s0, s0, s1
	s_add_i32 s0, s0, s30
	s_add_i32 s0, s0, s32
	v_cmp_ge_u32_e32 vcc, v21, v23
	v_cmp_ge_u32_e64 s[98:99], v20, v23
	v_cmp_ge_u32_e64 s[100:101], v22, v23
	s_bcnt1_i32_b64 s1, vcc
	s_bcnt1_i32_b64 s30, s[98:99]
	s_bcnt1_i32_b64 s32, s[100:101]
	s_add_i32 s0, s0, s1
	s_add_i32 s0, s0, s30
	s_add_i32 s0, s0, s32
	s_cmpk_gt_i32 s0, 0xff
	s_cselect_b32 s6, s28, s6
	s_add_i32 s7, s7, -1
	s_cmp_eq_u32 s7, -1
	s_cbranch_scc0 .LBB0_1096

; DI int ballot_cnt_ge(u32 a, u32 b) {
;   int t;
;   asm volatile("v_cmp_ge_u32 vcc, %1, %2\n\ts_bcnt1_i32_b64 %0, vcc" : "=s"(t) : "v"(a), "v"(b) : "vcc", "scc");
;   return t;
; }
; template <int NJ>
; DI u32 bisect256(const u32* row, int lane, int nw) {
;   u32 v[NJ];
; #pragma unroll
;   for (int j = 0; j < NJ; ++j) v[j] = (j < nw) ? row[j * 66 + lane + (lane >> 5)] : 0u;
;   u32 Tt = 0u;
;     ...
;     const u32 cand = Tt | (1u << bit);
;     int cnt = 0;
; #pragma unroll
;     for (int j = 0; j < NJ; ++j) cnt += ballot_cnt_ge(v[j], cand);
;     if (cnt >= 256) Tt = cand;
;   }
;   return Tt;
; }
.LBB0_1108:
	v_lshlrev_b32_e64 v17, v16, 1
	v_or_b32_e32 v17, v17, v8
	v_cmp_ge_u32_e32 vcc, v0, v17
	v_cmp_ge_u32_e64 s[98:99], v1, v17
	v_cmp_ge_u32_e64 s[100:101], v2, v17
	s_bcnt1_i32_b64 s7, vcc
	s_bcnt1_i32_b64 s30, s[98:99]
	s_bcnt1_i32_b64 s32, s[100:101]
	s_add_i32 s6, s7, s30
	s_add_i32 s6, s6, s32
	v_add_u32_e32 v16, -1, v16
	v_cmp_ge_u32_e32 vcc, v3, v17
	v_cmp_ge_u32_e64 s[98:99], v26, v17
	v_cmp_ge_u32_e64 s[100:101], v4, v17
	s_bcnt1_i32_b64 s7, vcc
	s_bcnt1_i32_b64 s30, s[98:99]
	s_bcnt1_i32_b64 s32, s[100:101]
	s_add_i32 s6, s6, s7
	s_add_i32 s6, s6, s30
	s_add_i32 s6, s6, s32
	v_cmp_ge_u32_e32 vcc, v5, v17
	v_cmp_ge_u32_e64 s[98:99], v6, v17
	v_cmp_ge_u32_e64 s[100:101], v7, v17
	s_bcnt1_i32_b64 s7, vcc
	s_bcnt1_i32_b64 s30, s[98:99]
	s_bcnt1_i32_b64 s32, s[100:101]
	s_add_i32 s6, s6, s7
	s_add_i32 s6, s6, s30
	s_add_i32 s6, s6, s32
	v_cmp_ge_u32_e32 vcc, v10, v17
	v_cmp_ge_u32_e64 s[98:99], v9, v17
	v_cmp_ge_u32_e64 s[100:101], v12, v17
	s_bcnt1_i32_b64 s7, vcc
	s_bcnt1_i32_b64 s30, s[98:99]
	s_bcnt1_i32_b64 s32, s[100:101]
	s_add_i32 s6, s6, s7
	s_add_i32 s6, s6, s30
	s_add_i32 s6, s6, s32
	s_waitcnt lgkmcnt(0)
	v_cmp_ge_u32_e32 vcc, v11, v17
	v_cmp_ge_u32_e64 s[98:99], v14, v17
	v_cmp_ge_u32_e64 s[100:101], v13, v17
	s_bcnt1_i32_b64 s7, vcc
	s_bcnt1_i32_b64 s30, s[98:99]
	s_bcnt1_i32_b64 s32, s[100:101]
	s_add_i32 s6, s6, s7
	s_add_i32 s6, s6, s30
	s_add_i32 s6, s6, s32
	v_cmp_ge_u32_e32 vcc, v15, v17
	s_bcnt1_i32_b64 s7, vcc
	s_add_i32 s6, s6, s7
	s_cmpk_gt_i32 s6, 0xff
	s_cselect_b64 vcc, -1, 0
	v_cndmask_b32_e32 v8, v8, v17, vcc
	v_lshlrev_b32_e64 v17, v16, 1
	v_or_b32_e32 v17, v17, v8
	v_cmp_ge_u32_e32 vcc, v0, v17
	v_cmp_ge_u32_e64 s[98:99], v1, v17
	v_cmp_ge_u32_e64 s[100:101], v2, v17
	s_bcnt1_i32_b64 s7, vcc
	s_bcnt1_i32_b64 s30, s[98:99]
	s_bcnt1_i32_b64 s32, s[100:101]
	s_add_i32 s6, s7, s30
	s_add_i32 s6, s6, s32
	v_cmp_ge_u32_e32 vcc, v3, v17
	v_cmp_ge_u32_e64 s[98:99], v26, v17
	v_cmp_ge_u32_e64 s[100:101], v4, v17
	s_bcnt1_i32_b64 s7, vcc
	s_bcnt1_i32_b64 s30, s[98:99]
	s_bcnt1_i32_b64 s32, s[100:101]
	s_add_i32 s6, s6, s7
	s_add_i32 s6, s6, s30
	s_add_i32 s6, s6, s32
	v_cmp_ge_u32_e32 vcc, v5, v17
	v_cmp_ge_u32_e64 s[98:99], v6, v17
	v_cmp_ge_u32_e64 s[100:101], v7, v17
	s_bcnt1_i32_b64 s7, vcc
	s_bcnt1_i32_b64 s30, s[98:99]
	s_bcnt1_i32_b64 s32, s[100:101]
	s_add_i32 s6, s6, s7
	s_add_i32 s6, s6, s30
	s_add_i32 s6, s6, s32
	v_cmp_ge_u32_e32 vcc, v10, v17
	v_cmp_ge_u32_e64 s[98:99], v9, v17
	v_cmp_ge_u32_e64 s[100:101], v12, v17
	s_bcnt1_i32_b64 s7, vcc
	s_bcnt1_i32_b64 s30, s[98:99]
	s_bcnt1_i32_b64 s32, s[100:101]
	s_add_i32 s6, s6, s7
	s_add_i32 s6, s6, s30
	s_add_i32 s6, s6, s32
	v_cmp_ge_u32_e32 vcc, v11, v17
	v_cmp_ge_u32_e64 s[98:99], v14, v17
	v_cmp_ge_u32_e64 s[100:101], v13, v17
	s_bcnt1_i32_b64 s7, vcc
	s_bcnt1_i32_b64 s30, s[98:99]
	s_bcnt1_i32_b64 s32, s[100:101]
	s_add_i32 s6, s6, s7
	s_add_i32 s6, s6, s30
	s_add_i32 s6, s6, s32
	v_cmp_ge_u32_e32 vcc, v15, v17
	s_bcnt1_i32_b64 s7, vcc
	s_add_i32 s6, s6, s7
	s_cmpk_gt_i32 s6, 0xff
	s_cselect_b64 vcc, -1, 0
	v_cndmask_b32_e32 v8, v8, v17, vcc
	v_subrev_co_u32_e32 v16, vcc, 1, v16
	s_and_b64 vcc, exec, vcc
	s_cbranch_vccz .LBB0_1108

; DI int ballot_cnt_ge(u32 a, u32 b) {
;   int t;
;   asm volatile("v_cmp_ge_u32 vcc, %1, %2\n\ts_bcnt1_i32_b64 %0, vcc" : "=s"(t) : "v"(a), "v"(b) : "vcc", "scc");
;   return t;
; }
; template <int NJ>
; DI u32 bisect256(const u32* row, int lane, int nw) {
;   u32 v[NJ];
; #pragma unroll
;   for (int j = 0; j < NJ; ++j) v[j] = (j < nw) ? row[j * 66 + lane + (lane >> 5)] : 0u;
;   u32 Tt = 0u;
;     ...
;     const u32 cand = Tt | (1u << bit);
;     int cnt = 0;
; #pragma unroll
;     for (int j = 0; j < NJ; ++j) cnt += ballot_cnt_ge(v[j], cand);
;     if (cnt >= 256) Tt = cand;
;   }
;   return Tt;
; }
.LBB0_1116:
	v_lshlrev_b32_e64 v9, v7, 1
	v_or_b32_e32 v9, v9, v8
	v_cmp_ge_u32_e32 vcc, v0, v9
	v_cmp_ge_u32_e64 s[98:99], v1, v9
	v_cmp_ge_u32_e64 s[100:101], v2, v9
	s_bcnt1_i32_b64 s7, vcc
	s_bcnt1_i32_b64 s30, s[98:99]
	s_bcnt1_i32_b64 s32, s[100:101]
	s_add_i32 s6, s7, s30
	s_add_i32 s6, s6, s32
	v_add_u32_e32 v7, -1, v7
	v_cmp_ge_u32_e32 vcc, v3, v9
	v_cmp_ge_u32_e64 s[98:99], v26, v9
	v_cmp_ge_u32_e64 s[100:101], v5, v9
	s_bcnt1_i32_b64 s7, vcc
	s_bcnt1_i32_b64 s30, s[98:99]
	s_bcnt1_i32_b64 s32, s[100:101]
	s_add_i32 s6, s6, s7
	s_add_i32 s6, s6, s30
	s_add_i32 s6, s6, s32
	s_waitcnt lgkmcnt(0)
	v_cmp_ge_u32_e32 vcc, v4, v9
	v_cmp_ge_u32_e64 s[98:99], v6, v9
	s_bcnt1_i32_b64 s7, vcc
	s_bcnt1_i32_b64 s30, s[98:99]
	s_add_i32 s6, s6, s7
	s_add_i32 s6, s6, s30
	s_cmpk_gt_i32 s6, 0xff
	s_cselect_b64 vcc, -1, 0
	v_cndmask_b32_e32 v8, v8, v9, vcc
	v_lshlrev_b32_e64 v9, v7, 1
	v_or_b32_e32 v9, v9, v8
	v_cmp_ge_u32_e32 vcc, v0, v9
	v_cmp_ge_u32_e64 s[98:99], v1, v9
	v_cmp_ge_u32_e64 s[100:101], v2, v9
	s_bcnt1_i32_b64 s7, vcc
	s_bcnt1_i32_b64 s30, s[98:99]
	s_bcnt1_i32_b64 s32, s[100:101]
	s_add_i32 s6, s7, s30
	s_add_i32 s6, s6, s32
	v_cmp_ge_u32_e32 vcc, v3, v9
	v_cmp_ge_u32_e64 s[98:99], v26, v9
	v_cmp_ge_u32_e64 s[100:101], v5, v9
	s_bcnt1_i32_b64 s7, vcc
	s_bcnt1_i32_b64 s30, s[98:99]
	s_bcnt1_i32_b64 s32, s[100:101]
	s_add_i32 s6, s6, s7
	s_add_i32 s6, s6, s30
	s_add_i32 s6, s6, s32
	v_cmp_ge_u32_e32 vcc, v4, v9
	v_cmp_ge_u32_e64 s[98:99], v6, v9
	s_bcnt1_i32_b64 s7, vcc
	s_bcnt1_i32_b64 s30, s[98:99]
	s_add_i32 s6, s6, s7
	s_add_i32 s6, s6, s30
	s_cmpk_gt_i32 s6, 0xff
	s_cselect_b64 vcc, -1, 0
	v_cndmask_b32_e32 v8, v8, v9, vcc
	v_subrev_co_u32_e32 v7, vcc, 1, v7
	s_and_b64 vcc, exec, vcc
	s_cbranch_vccz .LBB0_1116

; __global__ void __launch_bounds__(256, 2) fwd_megakernel(Params p) {
;   cg::grid_group grid = cg::this_grid();
;   __shared__ __attribute__((aligned(16))) unsigned char smem[SMEM_BYTES];
	.amdhsa_kernel _Z14fwd_megakernel6Params
		.amdhsa_group_segment_fixed_size 67600
		.amdhsa_private_segment_fixed_size 0
		.amdhsa_kernarg_size 776
		.amdhsa_user_sgpr_count 2
		.amdhsa_user_sgpr_dispatch_ptr 0
		.amdhsa_user_sgpr_queue_ptr 0
		.amdhsa_user_sgpr_kernarg_segment_ptr 1
		.amdhsa_user_sgpr_dispatch_id 0
		.amdhsa_user_sgpr_kernarg_preload_length 0
		.amdhsa_user_sgpr_kernarg_preload_offset 0
		.amdhsa_user_sgpr_private_segment_size 0
		.amdhsa_uses_dynamic_stack 0
		.amdhsa_enable_private_segment 0
		.amdhsa_system_sgpr_workgroup_id_x 1
		.amdhsa_system_sgpr_workgroup_id_y 0
		.amdhsa_system_sgpr_workgroup_id_z 0
		.amdhsa_system_sgpr_workgroup_info 0
		.amdhsa_system_vgpr_workitem_id 2
		.amdhsa_next_free_vgpr 256
		.amdhsa_next_free_sgpr 102
		.amdhsa_accum_offset 256
		.amdhsa_reserve_vcc 1
		.amdhsa_float_round_mode_32 0
		.amdhsa_float_round_mode_16_64 0
		.amdhsa_float_denorm_mode_32 3
		.amdhsa_float_denorm_mode_16_64 3
		.amdhsa_dx10_clamp 1
		.amdhsa_ieee_mode 1
		.amdhsa_fp16_overflow 0
		.amdhsa_tg_split 0
		.amdhsa_exception_fp_ieee_invalid_op 0
		.amdhsa_exception_fp_denorm_src 0
		.amdhsa_exception_fp_ieee_div_zero 0
		.amdhsa_exception_fp_ieee_overflow 0
		.amdhsa_exception_fp_ieee_underflow 0
		.amdhsa_exception_fp_ieee_inexact 0
		.amdhsa_exception_int_div_zero 0
	.end_amdhsa_kernel

; __global__ void __launch_bounds__(256, 2) fwd_megakernel(Params p) {
;   cg::grid_group grid = cg::this_grid();
;   __shared__ __attribute__((aligned(16))) unsigned char smem[SMEM_BYTES];
amdhsa.kernels:
  - .agpr_count:     0
    .args:
      - .offset:         0
        .size:           520
        .value_kind:     by_value
      - .offset:         520
        .size:           4
        .value_kind:     hidden_block_count_x
      - .offset:         524
        .size:           4
        .value_kind:     hidden_block_count_y
      - .offset:         528
        .size:           4
        .value_kind:     hidden_block_count_z
      - .offset:         532
        .size:           2
        .value_kind:     hidden_group_size_x
      - .offset:         534
        .size:           2
        .value_kind:     hidden_group_size_y
      - .offset:         536
        .size:           2
        .value_kind:     hidden_group_size_z
      - .offset:         538
        .size:           2
        .value_kind:     hidden_remainder_x
      - .offset:         540
        .size:           2
        .value_kind:     hidden_remainder_y
      - .offset:         542
        .size:           2
        .value_kind:     hidden_remainder_z
      - .offset:         560
        .size:           8
        .value_kind:     hidden_global_offset_x
      - .offset:         568
        .size:           8
        .value_kind:     hidden_global_offset_y
      - .offset:         576
        .size:           8
        .value_kind:     hidden_global_offset_z
      - .offset:         584
        .size:           2
        .value_kind:     hidden_grid_dims
      - .offset:         608
        .size:           8
        .value_kind:     hidden_multigrid_sync_arg
    .group_segment_fixed_size: 67600
    .kernarg_segment_align: 8
    .kernarg_segment_size: 776
    .language:       OpenCL C
    .language_version:
      - 2
      - 0
    .max_flat_workgroup_size: 256
    .name:           _Z14fwd_megakernel6Params
    .private_segment_fixed_size: 0
    .sgpr_count:     108
    .sgpr_spill_count: 16
    .symbol:         _Z14fwd_megakernel6Params.kd
    .uniform_work_group_size: 1
    .uses_dynamic_stack: false
    .vgpr_count:     256
    .vgpr_spill_count: 0
    .wavefront_size: 64
